# rwkv tiles: next-chunk global prefetch issued at the top of the chunk loop (before the light prep) instead of after it
# speedup vs baseline: 1.0437x; 1.0051x over previous
; template <bool DUAL>
; __device__ __forceinline__ void rwkv_tile(const Params& p, int l, int tile, unsigned char* smem) {
;     ...
;   __syncthreads();
;   for (int cix = cbeg; cix < cend; ++cix) {
;     int plo, slo, shi;
;     RW_GEOM(cix, plo, slo, shi);
.LBB0_1410:
	s_or_b64 exec, exec, s[48:49]
	s_cmpk_eq_i32 s52, 0x88
	s_mov_b32 s28, s52
	s_waitcnt vmcnt(0) lgkmcnt(0)
	s_barrier
	s_cbranch_scc1 .LBB0_1441
.LBB0_1411:
	s_add_i32 s52, s28, 1
	s_cmpk_eq_i32 s28, 0x87
	s_cbranch_scc1 .Lrw_du_nopf
	s_lshl_b32 s53, s52, 5
	s_sub_i32 s54, 0x11e0, s53
	s_and_b64 s[50:51], s[36:37], exec
	s_cselect_b32 s53, s53, s54
	s_add_i32 s54, s53, -1
	v_add_u32_e32 v30, s54, v97
	v_add_u32_e32 v28, 0xffffff00, v30
	v_cmp_gt_u32_e32 vcc, s31, v28
	v_mov_b32_e32 v28, v164
	v_mov_b32_e32 v29, v164
	s_and_b64 s[56:57], s[42:43], vcc
	v_mov_b64_e32 v[32:33], v[28:29]
	v_mov_b64_e32 v[34:35], v[28:29]
	s_and_saveexec_b64 s[50:51], s[56:57]
	s_cbranch_execz .LBB0_1414
	v_lshlrev_b32_e32 v30, 11, v30
	v_mov_b32_e32 v31, v164
	v_lshl_add_u64 v[30:31], v[80:81], 0, v[30:31]
	global_load_dwordx4 v[32:35], v[30:31], off

; template <bool DUAL>
; __device__ __forceinline__ void rwkv_tile(const Params& p, int l, int tile, unsigned char* smem) {
;     ...
; #pragma unroll
;     for (int k = 0; k < 2; ++k) {
;       const int i = (tid >> 4) + 16 * k;
;       const int ri = (d == 0) ? i + 1 : 32 - i;
;       const bf16_t* r0 = raw + ri * 192 + lc;
;       const bf16_t* q0 = pre + (ri - 1) * 192 + lc;
;       float rs[4], ksv[4], vs[4];
; #pragma unroll
;       for (int sl = 0; sl < 3; ++sl) {
;         const uint2 uc = *(const uint2*)(r0 + sl * 64), up = *(const uint2*)(r0 + sl * 64 - 192), un = *(const uint2*)(r0 + sl * 64 + 192);
;         const float4 m0 = (sl == 0) ? m0r : ((sl == 1) ? m0k : m0v);
;         const float4 m1 = (sl == 0) ? m1r : ((sl == 1) ? m1k : m1v);
;         float* dst = (sl == 0) ? rs : ((sl == 1) ? ksv : vs);
;         float u, a, n;
;         u = __uint_as_float(uc.x << 16); a = __uint_as_float(up.x << 16); n = __uint_as_float(un.x << 16);
;         dst[0] = u + m0.x * (a - u) + m1.x * (n - u);
;         u = __uint_as_float(uc.x & 0xffff0000u); a = __uint_as_float(up.x & 0xffff0000u); n = __uint_as_float(un.x & 0xffff0000u);
;         dst[1] = u + m0.y * (a - u) + m1.y * (n - u);
;         u = __uint_as_float(uc.y << 16); a = __uint_as_float(up.y << 16); n = __uint_as_float(un.y << 16);
;         dst[2] = u + m0.z * (a - u) + m1.z * (n - u);
;         u = __uint_as_float(uc.y & 0xffff0000u); a = __uint_as_float(up.y & 0xffff0000u); n = __uint_as_float(un.y & 0xffff0000u);
;         dst[3] = u + m0.w * (a - u) + m1.w * (n - u);
;       }
;       const uint2 ue = *(const uint2*)(q0), ua = *(const uint2*)(q0 + 64), uk = *(const uint2*)(q0 + 128);
;       const float ew[4] = {__uint_as_float(ue.x << 16), __uint_as_float(ue.x & 0xffff0000u), __uint_as_float(ue.y << 16), __uint_as_float(ue.y & 0xffff0000u)};
;       const float av[4] = {__uint_as_float(ua.x << 16), __uint_as_float(ua.x & 0xffff0000u), __uint_as_float(ua.y << 16), __uint_as_float(ua.y & 0xffff0000u)};
;       const float kk[4] = {__uint_as_float(uk.x << 16), __uint_as_float(uk.x & 0xffff0000u), __uint_as_float(uk.y << 16), __uint_as_float(uk.y & 0xffff0000u)};
;       const float kav[4] = {ka4.x, ka4.y, ka4.z, ka4.w};
;       float4 o0, o1, o2, o3, o4, o5;
.Lrw_du_nopf:
	ds_read2_b64 v[60:63], v107 offset1:16
	ds_read_b64 v[72:73], v108
	ds_read2_b64 v[64:67], v107 offset0:32 offset1:48
	ds_read_b64 v[76:77], v109
	ds_read_b64 v[78:79], v110
	ds_read_b64 v[122:123], v111 offset:12928
	ds_read2_b64 v[68:71], v107 offset0:64 offset1:80
	s_waitcnt lgkmcnt(6)
	v_lshlrev_b32_e32 v74, 16, v60
	v_and_b32_e32 v75, 0xffff0000, v60
	v_add_u32_e32 v60, 0x3000, v111
	v_lshlrev_b32_e32 v128, 16, v61
	v_and_b32_e32 v129, 0xffff0000, v61
	v_lshlrev_b32_e32 v132, 16, v62
	v_and_b32_e32 v133, 0xffff0000, v62
	v_lshlrev_b32_e32 v138, 16, v63
	v_and_b32_e32 v139, 0xffff0000, v63
	ds_read2_b64 v[60:63], v60 offset0:48 offset1:64
	s_waitcnt lgkmcnt(5)
	v_lshlrev_b32_e32 v142, 16, v64
	v_and_b32_e32 v143, 0xffff0000, v64
	s_waitcnt lgkmcnt(1)
	v_lshlrev_b32_e32 v136, 16, v68
	v_and_b32_e32 v137, 0xffff0000, v68
	s_waitcnt lgkmcnt(0)
	v_lshlrev_b32_e32 v64, 16, v60
	v_and_b32_e32 v60, 0xffff0000, v60
	v_lshlrev_b32_e32 v68, 16, v61
	v_mul_f32_e32 v60, 0xbfb8aa3b, v60
	v_lshlrev_b32_e32 v130, 16, v67
	v_and_b32_e32 v131, 0xffff0000, v67
	v_and_b32_e32 v61, 0xffff0000, v61
	v_exp_f32_e32 v67, v60
	v_mul_f32_e32 v60, 0xbfb8aa3b, v68
	v_mul_f32_e32 v64, 0xbfb8aa3b, v64
	v_exp_f32_e32 v68, v60
	v_mul_f32_e32 v60, 0xbfb8aa3b, v61
	v_lshlrev_b32_e32 v126, 16, v66
	v_and_b32_e32 v127, 0xffff0000, v66
	v_lshlrev_b32_e32 v140, 16, v69
	v_and_b32_e32 v141, 0xffff0000, v69
	v_exp_f32_e32 v66, v64
	v_exp_f32_e32 v69, v60
	v_lshlrev_b32_e32 v121, 16, v62
	v_lshlrev_b32_e32 v150, 16, v123
	v_lshlrev_b32_e32 v153, 16, v63
	ds_write_b128 v119, v[66:69] offset:25344
	v_and_b32_e32 v67, 16, v62
	v_and_b32_e32 v66, 0xffff0000, v122
	v_lshlrev_b32_e32 v68, 16, v122
	v_and_b32_e32 v69, 0xffff0000, v62
	v_pk_mov_b32 v[60:61], v[120:121], v[66:67] op_sel:[1,0]
	v_and_b32_e32 v155, 16, v63
	v_and_b32_e32 v154, 0xffff0000, v123
	v_lshlrev_b32_e32 v134, 16, v76
	v_and_b32_e32 v135, 0xffff0000, v76
	v_lshlrev_b32_e32 v148, 16, v65
	v_and_b32_e32 v149, 0xffff0000, v65
	v_pk_mul_f32 v[60:61], v[68:69], v[60:61]
	v_and_b32_e32 v151, 0xffff0000, v63
	v_pk_mov_b32 v[62:63], v[152:153], v[154:155] op_sel:[1,0]
	v_mov_b32_e32 v64, v68
	v_mov_b32_e32 v65, v66
	v_mov_b32_e32 v66, v150
	v_mov_b32_e32 v67, v154
	v_pk_mul_f32 v[62:63], v[150:151], v[62:63]
	ds_write_b128 v119, v[64:67] offset:25600
	ds_write_b128 v119, v[60:63] offset:25856
	v_pk_add_f32 v[60:61], v[134:135], v[132:133] neg_lo:[0,1] neg_hi:[0,1]
	v_pk_add_f32 v[62:63], v[136:137], v[132:133] neg_lo:[0,1] neg_hi:[0,1]

; template <bool DUAL>
; __device__ __forceinline__ void rwkv_tile(const Params& p, int l, int tile, unsigned char* smem) {
;     ...
;       for (int sl = 0; sl < 3; ++sl) {
;         const uint2 uc = *(const uint2*)(r0 + sl * 64), up = *(const uint2*)(r0 + sl * 64 - 192), un = *(const uint2*)(r0 + sl * 64 + 192);
;         const float4 m0 = (sl == 0) ? m0r : ((sl == 1) ? m0k : m0v);
;         const float4 m1 = (sl == 0) ? m1r : ((sl == 1) ? m1k : m1v);
;         float* dst = (sl == 0) ? rs : ((sl == 1) ? ksv : vs);
;         float u, a, n;
;         u = __uint_as_float(uc.x << 16); a = __uint_as_float(up.x << 16); n = __uint_as_float(un.x << 16);
;         dst[0] = u + m0.x * (a - u) + m1.x * (n - u);
;         u = __uint_as_float(uc.x & 0xffff0000u); a = __uint_as_float(up.x & 0xffff0000u); n = __uint_as_float(un.x & 0xffff0000u);
;         dst[1] = u + m0.y * (a - u) + m1.y * (n - u);
;         u = __uint_as_float(uc.y << 16); a = __uint_as_float(up.y << 16); n = __uint_as_float(un.y << 16);
;         dst[2] = u + m0.z * (a - u) + m1.z * (n - u);
;         u = __uint_as_float(uc.y & 0xffff0000u); a = __uint_as_float(up.y & 0xffff0000u); n = __uint_as_float(un.y & 0xffff0000u);
;         dst[3] = u + m0.w * (a - u) + m1.w * (n - u);
;       }
;       const uint2 ue = *(const uint2*)(q0), ua = *(const uint2*)(q0 + 64), uk = *(const uint2*)(q0 + 128);
;       const float ew[4] = {__uint_as_float(ue.x << 16), __uint_as_float(ue.x & 0xffff0000u), __uint_as_float(ue.y << 16), __uint_as_float(ue.y & 0xffff0000u)};
;       const float av[4] = {__uint_as_float(ua.x << 16), __uint_as_float(ua.x & 0xffff0000u), __uint_as_float(ua.y << 16), __uint_as_float(ua.y & 0xffff0000u)};
;       const float kk[4] = {__uint_as_float(uk.x << 16), __uint_as_float(uk.x & 0xffff0000u), __uint_as_float(uk.y << 16), __uint_as_float(uk.y & 0xffff0000u)};
;       const float kav[4] = {ka4.x, ka4.y, ka4.z, ka4.w};
;       float4 o0, o1, o2, o3, o4, o5;
;       float* f0 = (float*)&o0; float* f1 = (float*)&o1; float* f2 = (float*)&o2; float* f3 = (float*)&o3; float* f4 = (float*)&o4; float* f5 = (float*)&o5;
; #pragma unroll
;       for (int e = 0; e < 4; ++e) {
;         f0[e] = __expf(-ew[e]);
;         f1[e] = kk[e];
;         f2[e] = kk[e] * av[e];
;         f3[e] = ksv[e] * (1.f + (av[e] - 1.f) * kav[e]);
	v_pk_fma_f32 v[60:61], v[12:13], v[60:61], v[132:133]
	v_mov_b32_e32 v68, v121

; template <bool DUAL>
; __device__ __forceinline__ void rwkv_tile(const Params& p, int l, int tile, unsigned char* smem) {
;     ...
;       for (int sl = 0; sl < 3; ++sl) {
;         const uint2 uc = *(const uint2*)(r0 + sl * 64), up = *(const uint2*)(r0 + sl * 64 - 192), un = *(const uint2*)(r0 + sl * 64 + 192);
;         const float4 m0 = (sl == 0) ? m0r : ((sl == 1) ? m0k : m0v);
;         const float4 m1 = (sl == 0) ? m1r : ((sl == 1) ? m1k : m1v);
;         float* dst = (sl == 0) ? rs : ((sl == 1) ? ksv : vs);
;         float u, a, n;
;         u = __uint_as_float(uc.x << 16); a = __uint_as_float(up.x << 16); n = __uint_as_float(un.x << 16);
;         dst[0] = u + m0.x * (a - u) + m1.x * (n - u);
;         u = __uint_as_float(uc.x & 0xffff0000u); a = __uint_as_float(up.x & 0xffff0000u); n = __uint_as_float(un.x & 0xffff0000u);
;         dst[1] = u + m0.y * (a - u) + m1.y * (n - u);
;         u = __uint_as_float(uc.y << 16); a = __uint_as_float(up.y << 16); n = __uint_as_float(un.y << 16);
;         dst[2] = u + m0.z * (a - u) + m1.z * (n - u);
;         u = __uint_as_float(uc.y & 0xffff0000u); a = __uint_as_float(up.y & 0xffff0000u); n = __uint_as_float(un.y & 0xffff0000u);
;         dst[3] = u + m0.w * (a - u) + m1.w * (n - u);
;       }
;       const uint2 ue = *(const uint2*)(q0), ua = *(const uint2*)(q0 + 64), uk = *(const uint2*)(q0 + 128);
;       const float ew[4] = {__uint_as_float(ue.x << 16), __uint_as_float(ue.x & 0xffff0000u), __uint_as_float(ue.y << 16), __uint_as_float(ue.y & 0xffff0000u)};
;       const float av[4] = {__uint_as_float(ua.x << 16), __uint_as_float(ua.x & 0xffff0000u), __uint_as_float(ua.y << 16), __uint_as_float(ua.y & 0xffff0000u)};
;       const float kk[4] = {__uint_as_float(uk.x << 16), __uint_as_float(uk.x & 0xffff0000u), __uint_as_float(uk.y << 16), __uint_as_float(uk.y & 0xffff0000u)};
;       const float kav[4] = {ka4.x, ka4.y, ka4.z, ka4.w};
;       float4 o0, o1, o2, o3, o4, o5;
;       float* f0 = (float*)&o0; float* f1 = (float*)&o1; float* f2 = (float*)&o2; float* f3 = (float*)&o3; float* f4 = (float*)&o4; float* f5 = (float*)&o5;
; #pragma unroll
;       for (int e = 0; e < 4; ++e) {
;         f0[e] = __expf(-ew[e]);
;         f1[e] = kk[e];
;         f2[e] = kk[e] * av[e];
;         f3[e] = ksv[e] * (1.f + (av[e] - 1.f) * kav[e]);
	v_pk_fma_f32 v[60:61], v[20:21], v[62:63], v[60:61]
	v_pk_add_f32 v[62:63], v[68:69], -1.0 op_sel_hi:[1,0]
	v_lshlrev_b32_e32 v76, 16, v77
	v_and_b32_e32 v77, 0xffff0000, v77

; template <bool DUAL>
; __device__ __forceinline__ void rwkv_tile(const Params& p, int l, int tile, unsigned char* smem) {
;     ...
; #pragma unroll
;     for (int k = 0; k < 2; ++k) {
;       const int i = (tid >> 4) + 16 * k;
;       const int ri = (d == 0) ? i + 1 : 32 - i;
;       const bf16_t* r0 = raw + ri * 192 + lc;
;       const bf16_t* q0 = pre + (ri - 1) * 192 + lc;
;       float rs[4], ksv[4], vs[4];
; #pragma unroll
;       for (int sl = 0; sl < 3; ++sl) {
;         const uint2 uc = *(const uint2*)(r0 + sl * 64), up = *(const uint2*)(r0 + sl * 64 - 192), un = *(const uint2*)(r0 + sl * 64 + 192);
;         const float4 m0 = (sl == 0) ? m0r : ((sl == 1) ? m0k : m0v);
;         const float4 m1 = (sl == 0) ? m1r : ((sl == 1) ? m1k : m1v);
;         float* dst = (sl == 0) ? rs : ((sl == 1) ? ksv : vs);
;         float u, a, n;
;         u = __uint_as_float(uc.x << 16); a = __uint_as_float(up.x << 16); n = __uint_as_float(un.x << 16);
;         dst[0] = u + m0.x * (a - u) + m1.x * (n - u);
;         u = __uint_as_float(uc.x & 0xffff0000u); a = __uint_as_float(up.x & 0xffff0000u); n = __uint_as_float(un.x & 0xffff0000u);
;         dst[1] = u + m0.y * (a - u) + m1.y * (n - u);
;         u = __uint_as_float(uc.y << 16); a = __uint_as_float(up.y << 16); n = __uint_as_float(un.y << 16);
;         dst[2] = u + m0.z * (a - u) + m1.z * (n - u);
;         u = __uint_as_float(uc.y & 0xffff0000u); a = __uint_as_float(up.y & 0xffff0000u); n = __uint_as_float(un.y & 0xffff0000u);
;         dst[3] = u + m0.w * (a - u) + m1.w * (n - u);
;       }
;       const uint2 ue = *(const uint2*)(q0), ua = *(const uint2*)(q0 + 64), uk = *(const uint2*)(q0 + 128);
;       const float ew[4] = {__uint_as_float(ue.x << 16), __uint_as_float(ue.x & 0xffff0000u), __uint_as_float(ue.y << 16), __uint_as_float(ue.y & 0xffff0000u)};
;       const float av[4] = {__uint_as_float(ua.x << 16), __uint_as_float(ua.x & 0xffff0000u), __uint_as_float(ua.y << 16), __uint_as_float(ua.y & 0xffff0000u)};
;       const float kk[4] = {__uint_as_float(uk.x << 16), __uint_as_float(uk.x & 0xffff0000u), __uint_as_float(uk.y << 16), __uint_as_float(uk.y & 0xffff0000u)};
;       const float kav[4] = {ka4.x, ka4.y, ka4.z, ka4.w};
;       float4 o0, o1, o2, o3, o4, o5;
	v_pk_fma_f32 v[62:63], v[24:25], v[62:63], 1.0 op_sel_hi:[1,1,0]
	v_pk_add_f32 v[64:65], v[140:141], v[138:139] neg_lo:[0,1] neg_hi:[0,1]
	v_pk_mul_f32 v[60:61], v[60:61], v[62:63]
	v_pk_add_f32 v[62:63], v[76:77], v[138:139] neg_lo:[0,1] neg_hi:[0,1]
	v_mov_b32_e32 v150, v153
	v_pk_fma_f32 v[62:63], v[14:15], v[62:63], v[138:139]
	v_lshlrev_b32_e32 v124, 16, v72
	v_pk_fma_f32 v[62:63], v[22:23], v[64:65], v[62:63]
	v_pk_add_f32 v[64:65], v[150:151], -1.0 op_sel_hi:[1,0]
	v_and_b32_e32 v125, 0xffff0000, v72
	v_pk_fma_f32 v[64:65], v[26:27], v[64:65], 1.0 op_sel_hi:[1,1,0]
	v_lshlrev_b32_e32 v72, 16, v73
	v_pk_mul_f32 v[62:63], v[62:63], v[64:65]
	ds_write_b128 v119, v[60:63] offset:26112
	v_pk_add_f32 v[60:61], v[124:125], v[74:75] neg_lo:[0,1] neg_hi:[0,1]
	v_and_b32_e32 v73, 0xffff0000, v73
	v_pk_fma_f32 v[60:61], v[8:9], v[60:61], v[74:75]
	v_pk_add_f32 v[62:63], v[126:127], v[74:75] neg_lo:[0,1] neg_hi:[0,1]
	v_pk_add_f32 v[64:65], v[130:131], v[128:129] neg_lo:[0,1] neg_hi:[0,1]
	v_pk_fma_f32 v[60:61], v[0:1], v[62:63], v[60:61]
	v_pk_add_f32 v[62:63], v[72:73], v[128:129] neg_lo:[0,1] neg_hi:[0,1]
	v_lshlrev_b32_e32 v144, 16, v78
	v_pk_fma_f32 v[62:63], v[10:11], v[62:63], v[128:129]
	v_and_b32_e32 v145, 0xffff0000, v78
	v_pk_fma_f32 v[62:63], v[2:3], v[64:65], v[62:63]
	v_lshlrev_b32_e32 v146, 16, v70
	v_and_b32_e32 v147, 0xffff0000, v70
	ds_write_b128 v119, v[60:63] offset:26368
	v_pk_add_f32 v[60:61], v[144:145], v[142:143] neg_lo:[0,1] neg_hi:[0,1]
	v_lshlrev_b32_e32 v78, 16, v79
	v_and_b32_e32 v79, 0xffff0000, v79
	v_pk_fma_f32 v[60:61], v[4:5], v[60:61], v[142:143]
	v_pk_add_f32 v[62:63], v[146:147], v[142:143] neg_lo:[0,1] neg_hi:[0,1]
	v_lshlrev_b32_e32 v70, 16, v71
	v_and_b32_e32 v71, 0xffff0000, v71
	v_pk_fma_f32 v[60:61], v[16:17], v[62:63], v[60:61]
	v_pk_add_f32 v[62:63], v[78:79], v[148:149] neg_lo:[0,1] neg_hi:[0,1]
	v_pk_add_f32 v[64:65], v[70:71], v[148:149] neg_lo:[0,1] neg_hi:[0,1]
	v_pk_fma_f32 v[62:63], v[6:7], v[62:63], v[148:149]
	s_add_i32 s52, s28, 1
	v_pk_fma_f32 v[62:63], v[18:19], v[64:65], v[62:63]
	ds_write_b128 v119, v[60:63] offset:26624
	ds_read2_b64 v[60:63], v112 offset1:16
	ds_read_b64 v[72:73], v113
	ds_read2_b64 v[64:67], v112 offset0:32 offset1:48
	ds_read_b64 v[76:77], v114
	ds_read_b64 v[78:79], v115
	ds_read_b64 v[122:123], v116 offset:12928
	ds_read2_b64 v[68:71], v112 offset0:64 offset1:80
	s_waitcnt lgkmcnt(6)
	v_lshlrev_b32_e32 v74, 16, v60
	v_and_b32_e32 v75, 0xffff0000, v60
	v_add_u32_e32 v60, 0x3000, v116
	v_lshlrev_b32_e32 v128, 16, v61
	v_and_b32_e32 v129, 0xffff0000, v61
	v_lshlrev_b32_e32 v132, 16, v62
	v_and_b32_e32 v133, 0xffff0000, v62
	v_lshlrev_b32_e32 v138, 16, v63
	v_and_b32_e32 v139, 0xffff0000, v63
	ds_read2_b64 v[60:63], v60 offset0:48 offset1:64
	s_waitcnt lgkmcnt(5)
	v_lshlrev_b32_e32 v142, 16, v64
	v_and_b32_e32 v143, 0xffff0000, v64
	s_waitcnt lgkmcnt(1)
	v_lshlrev_b32_e32 v136, 16, v68
	v_and_b32_e32 v137, 0xffff0000, v68
	s_waitcnt lgkmcnt(0)
; template <bool DUAL>
; __device__ __forceinline__ void rwkv_tile(const Params& p, int l, int tile, unsigned char* smem) {
;     ...
; #pragma unroll
;     for (int k = 0; k < 2; ++k) {
;       const int i = (tid >> 4) + 16 * k;
;       const int ri = (d == 0) ? i + 1 : 32 - i;
;       const bf16_t* r0 = raw + ri * 192 + lc;
;       const bf16_t* q0 = pre + (ri - 1) * 192 + lc;
;       float rs[4], ksv[4], vs[4];
; #pragma unroll
;       for (int sl = 0; sl < 3; ++sl) {
;         const uint2 uc = *(const uint2*)(r0 + sl * 64), up = *(const uint2*)(r0 + sl * 64 - 192), un = *(const uint2*)(r0 + sl * 64 + 192);
;         const float4 m0 = (sl == 0) ? m0r : ((sl == 1) ? m0k : m0v);
;         const float4 m1 = (sl == 0) ? m1r : ((sl == 1) ? m1k : m1v);
;         float* dst = (sl == 0) ? rs : ((sl == 1) ? ksv : vs);
;         float u, a, n;
;         u = __uint_as_float(uc.x << 16); a = __uint_as_float(up.x << 16); n = __uint_as_float(un.x << 16);
;         dst[0] = u + m0.x * (a - u) + m1.x * (n - u);
;         u = __uint_as_float(uc.x & 0xffff0000u); a = __uint_as_float(up.x & 0xffff0000u); n = __uint_as_float(un.x & 0xffff0000u);
;         dst[1] = u + m0.y * (a - u) + m1.y * (n - u);
;         u = __uint_as_float(uc.y << 16); a = __uint_as_float(up.y << 16); n = __uint_as_float(un.y << 16);
;         dst[2] = u + m0.z * (a - u) + m1.z * (n - u);
;         u = __uint_as_float(uc.y & 0xffff0000u); a = __uint_as_float(up.y & 0xffff0000u); n = __uint_as_float(un.y & 0xffff0000u);
;         dst[3] = u + m0.w * (a - u) + m1.w * (n - u);
;       }
;       const uint2 ue = *(const uint2*)(q0), ua = *(const uint2*)(q0 + 64), uk = *(const uint2*)(q0 + 128);
;       const float ew[4] = {__uint_as_float(ue.x << 16), __uint_as_float(ue.x & 0xffff0000u), __uint_as_float(ue.y << 16), __uint_as_float(ue.y & 0xffff0000u)};
;       const float av[4] = {__uint_as_float(ua.x << 16), __uint_as_float(ua.x & 0xffff0000u), __uint_as_float(ua.y << 16), __uint_as_float(ua.y & 0xffff0000u)};
;       const float kk[4] = {__uint_as_float(uk.x << 16), __uint_as_float(uk.x & 0xffff0000u), __uint_as_float(uk.y << 16), __uint_as_float(uk.y & 0xffff0000u)};
;       const float kav[4] = {ka4.x, ka4.y, ka4.z, ka4.w};
;       float4 o0, o1, o2, o3, o4, o5;
	v_lshlrev_b32_e32 v64, 16, v60
	v_and_b32_e32 v60, 0xffff0000, v60
	v_lshlrev_b32_e32 v68, 16, v61
	v_mul_f32_e32 v60, 0xbfb8aa3b, v60
	v_lshlrev_b32_e32 v130, 16, v67
	v_and_b32_e32 v131, 0xffff0000, v67
	v_and_b32_e32 v61, 0xffff0000, v61
	v_exp_f32_e32 v67, v60
	v_mul_f32_e32 v60, 0xbfb8aa3b, v68
	v_mul_f32_e32 v64, 0xbfb8aa3b, v64
	v_exp_f32_e32 v68, v60
	v_mul_f32_e32 v60, 0xbfb8aa3b, v61
	v_lshlrev_b32_e32 v126, 16, v66
	v_and_b32_e32 v127, 0xffff0000, v66
	v_lshlrev_b32_e32 v140, 16, v69
	v_and_b32_e32 v141, 0xffff0000, v69
	v_exp_f32_e32 v66, v64
	v_exp_f32_e32 v69, v60
	v_lshlrev_b32_e32 v121, 16, v62
	v_lshlrev_b32_e32 v150, 16, v123
	v_lshlrev_b32_e32 v153, 16, v63
	ds_write_b128 v119, v[66:69] offset:49920
	v_and_b32_e32 v67, 16, v62
	v_and_b32_e32 v66, 0xffff0000, v122
	v_lshlrev_b32_e32 v68, 16, v122
	v_and_b32_e32 v69, 0xffff0000, v62
	v_pk_mov_b32 v[60:61], v[120:121], v[66:67] op_sel:[1,0]
	v_and_b32_e32 v155, 16, v63
	v_and_b32_e32 v154, 0xffff0000, v123
	v_lshlrev_b32_e32 v134, 16, v76
	v_and_b32_e32 v135, 0xffff0000, v76
	v_lshlrev_b32_e32 v148, 16, v65
	v_and_b32_e32 v149, 0xffff0000, v65
	v_pk_mul_f32 v[60:61], v[68:69], v[60:61]
	v_and_b32_e32 v151, 0xffff0000, v63
	v_pk_mov_b32 v[62:63], v[152:153], v[154:155] op_sel:[1,0]
	v_mov_b32_e32 v64, v68
	v_mov_b32_e32 v65, v66
	v_mov_b32_e32 v66, v150
	v_mov_b32_e32 v67, v154
	v_pk_mul_f32 v[62:63], v[150:151], v[62:63]
	ds_write_b128 v119, v[64:67] offset:50176
	ds_write_b128 v119, v[60:63] offset:50432
	v_pk_add_f32 v[60:61], v[134:135], v[132:133] neg_lo:[0,1] neg_hi:[0,1]
	v_pk_add_f32 v[62:63], v[136:137], v[132:133] neg_lo:[0,1] neg_hi:[0,1]
	v_pk_fma_f32 v[60:61], v[12:13], v[60:61], v[132:133]
	v_mov_b32_e32 v68, v121
	v_pk_fma_f32 v[60:61], v[20:21], v[62:63], v[60:61]
	v_pk_add_f32 v[62:63], v[68:69], -1.0 op_sel_hi:[1,0]
	v_lshlrev_b32_e32 v76, 16, v77
	v_and_b32_e32 v77, 0xffff0000, v77
	v_pk_fma_f32 v[62:63], v[24:25], v[62:63], 1.0 op_sel_hi:[1,1,0]
	v_pk_add_f32 v[64:65], v[140:141], v[138:139] neg_lo:[0,1] neg_hi:[0,1]
	v_pk_mul_f32 v[60:61], v[60:61], v[62:63]
	v_pk_add_f32 v[62:63], v[76:77], v[138:139] neg_lo:[0,1] neg_hi:[0,1]
	v_mov_b32_e32 v150, v153
	v_pk_fma_f32 v[62:63], v[14:15], v[62:63], v[138:139]
	v_lshlrev_b32_e32 v124, 16, v72
	v_pk_fma_f32 v[62:63], v[22:23], v[64:65], v[62:63]
	v_pk_add_f32 v[64:65], v[150:151], -1.0 op_sel_hi:[1,0]
	v_and_b32_e32 v125, 0xffff0000, v72
	v_pk_fma_f32 v[64:65], v[26:27], v[64:65], 1.0 op_sel_hi:[1,1,0]
	v_lshlrev_b32_e32 v72, 16, v73
	v_pk_mul_f32 v[62:63], v[62:63], v[64:65]
	ds_write_b128 v119, v[60:63] offset:50688
	v_pk_add_f32 v[60:61], v[124:125], v[74:75] neg_lo:[0,1] neg_hi:[0,1]
	v_and_b32_e32 v73, 0xffff0000, v73
	v_pk_fma_f32 v[60:61], v[8:9], v[60:61], v[74:75]
	v_pk_add_f32 v[62:63], v[126:127], v[74:75] neg_lo:[0,1] neg_hi:[0,1]
	v_pk_add_f32 v[64:65], v[130:131], v[128:129] neg_lo:[0,1] neg_hi:[0,1]
	v_pk_fma_f32 v[60:61], v[0:1], v[62:63], v[60:61]
	v_pk_add_f32 v[62:63], v[72:73], v[128:129] neg_lo:[0,1] neg_hi:[0,1]
	v_lshlrev_b32_e32 v144, 16, v78
	v_pk_fma_f32 v[62:63], v[10:11], v[62:63], v[128:129]
	v_and_b32_e32 v145, 0xffff0000, v78
	v_pk_fma_f32 v[62:63], v[2:3], v[64:65], v[62:63]
	v_lshlrev_b32_e32 v146, 16, v70
	v_and_b32_e32 v147, 0xffff0000, v70
	ds_write_b128 v119, v[60:63] offset:50944
	v_pk_add_f32 v[60:61], v[144:145], v[142:143] neg_lo:[0,1] neg_hi:[0,1]
	v_lshlrev_b32_e32 v78, 16, v79
	v_and_b32_e32 v79, 0xffff0000, v79
	v_pk_fma_f32 v[60:61], v[4:5], v[60:61], v[142:143]
	v_pk_add_f32 v[62:63], v[146:147], v[142:143] neg_lo:[0,1] neg_hi:[0,1]
	v_lshlrev_b32_e32 v70, 16, v71
	v_and_b32_e32 v71, 0xffff0000, v71
	v_pk_fma_f32 v[60:61], v[16:17], v[62:63], v[60:61]
	v_pk_add_f32 v[62:63], v[78:79], v[148:149] neg_lo:[0,1] neg_hi:[0,1]
	v_pk_add_f32 v[64:65], v[70:71], v[148:149] neg_lo:[0,1] neg_hi:[0,1]
	v_pk_fma_f32 v[62:63], v[6:7], v[62:63], v[148:149]
	s_cmpk_lg_i32 s28, 0x87
	v_pk_fma_f32 v[62:63], v[18:19], v[64:65], v[62:63]
	s_cselect_b64 s[48:49], -1, 0
	s_cmpk_eq_i32 s28, 0x87
	ds_write_b128 v119, v[60:63] offset:51200
	s_waitcnt lgkmcnt(0)
	s_barrier

; template <bool DUAL>
; __device__ __forceinline__ void rwkv_tile(const Params& p, int l, int tile, unsigned char* smem) {
;     ...
;   const int row = rg * 16 + w * 4 + fq;
;   const int c0 = fr * 4;
;   const int ld2 = l * 2 + d;
;   const size_t rowbase = (size_t)b * TPB;
;   const int lc = (tid & 15) * 4;
;   const float* mu0 = p.rwkv_mu + (size_t)(l * 2 + 0) * 1024 + h * 64 + lc;
;   const float* mu1 = p.rwkv_mu + (size_t)(l * 2 + 1) * 1024 + h * 64 + lc;
;   const float4 m0r = *(const float4*)mu0, m1r = *(const float4*)mu1;
;   const float4 m0k = *(const float4*)(mu0 + 256), m1k = *(const float4*)(mu1 + 256);
;   const float4 m0v = *(const float4*)(mu0 + 512), m1v = *(const float4*)(mu1 + 512);
;   const float4 ka4 = *(const float4*)(p.rwkv_k_a + ld2 * 256 + h * 64 + lc);
;   v2f sA = {0.f, 0.f}, sB = {0.f, 0.f};
;   v2f iA = {(row == c0) ? 1.f : 0.f, (row == c0 + 1) ? 1.f : 0.f}, iB = {(row == c0 + 2) ? 1.f : 0.f, (row == c0 + 3) ? 1.f : 0.f};
;   const int pcc = tid % 24, prow = tid / 24;
;   const bool pact = tid < 240;
;   const bf16_t* rbase_g = p.PR + rowbase * 1024 + (pcc >> 3) * 256 + h * 64 + (pcc & 7) * 8;
;     ...
;   __syncthreads();
;   for (int cix = cbeg; cix < cend; ++cix) {
;     int plo, slo, shi;
;     RW_GEOM(cix, plo, slo, shi);
; #pragma unroll
;     for (int k = 0; k < 2; ++k) {
;       const int i = (tid >> 4) + 16 * k;
;       const int ri = (d == 0) ? i + 1 : 32 - i;
;       const bf16_t* r0 = raw + ri * 192 + lc;
;       const bf16_t* q0 = pre + (ri - 1) * 192 + lc;
.LBB0_1467:
	s_or_b64 exec, exec, s[50:51]
	v_and_b32_e32 v98, 15, v61
	v_bfe_u32 v66, v61, 4, 2
	v_ashrrev_i32_e32 v61, 4, v61
	v_lshl_add_u32 v62, v62, 1, 0
	v_and_b32_e32 v67, -4, v61
	v_readlane_b32 s0, v253, 62
	v_lshl_add_u32 v102, v64, 1, v62
	v_lshl_add_u32 v103, v65, 1, v62
	v_add_u32_e32 v64, 1, v61
	v_sub_u32_e32 v65, 32, v61
	v_add_u32_e32 v67, s0, v67
	v_lshlrev_b32_e32 v60, 1, v60
	s_movk_i32 s0, 0x180
	v_cndmask_b32_e64 v64, v65, v64, s[36:37]
	v_add_u32_e32 v68, 0, v60
	v_mul_lo_u32 v64, v64, s0
	s_movk_i32 s1, 0x600
	v_add_u32_e32 v104, v68, v64
	v_add3_u32 v108, 0, v64, v60
	v_mul_lo_u32 v64, v61, s1
	v_add_u32_e32 v65, 17, v61
	v_sub_u32_e32 v61, 16, v61
	v_cndmask_b32_e64 v61, v61, v65, s[36:37]
	v_or_b32_e32 v88, v67, v66
	v_lshl_add_u32 v101, v63, 1, v62
	v_mul_lo_u32 v63, v96, s0
	v_mul_lo_u32 v61, v61, s0
	v_readlane_b32 s0, v254, 35
	v_ashrrev_i32_e32 v89, 31, v88
	v_readlane_b32 s1, v254, 36
	v_add_u32_e32 v69, v68, v60
	v_add3_u32 v113, 0, v61, v60
	v_lshl_add_u64 v[90:91], v[88:89], 1, s[0:1]
	v_add_u32_e32 v60, v67, v66
	v_readlane_b32 s0, v255, 26
	v_lshlrev_b32_e32 v70, 4, v98
	v_add_u32_e32 v109, v68, v61
	v_lshl_add_u32 v89, v60, 2, s0
	v_readlane_b32 s0, v255, 27
	v_mov_b32_e32 v165, v164
	v_lshlrev_b32_e32 v97, 2, v98
	v_add_u32_e32 v99, 0, v70
	v_lshl_add_u32 v100, v88, 2, 0
	v_add_u32_e32 v105, 0xfffffe80, v104
	v_add_u32_e32 v106, 0xffffff00, v104
	v_add_u32_e32 v107, 0xffffff80, v104
	v_add_u32_e32 v110, 0xfffffe80, v109
	v_add_u32_e32 v111, 0xffffff00, v109
	v_add_u32_e32 v112, 0xffffff80, v109
	v_add_u32_e32 v114, s0, v70
	v_add_u32_e32 v115, v69, v64
	v_add_u32_e32 v116, v62, v63
	v_mov_b64_e32 v[60:61], v[164:165]
	v_mov_b64_e32 v[62:63], v[164:165]
	v_readlane_b32 s28, v254, 17
	s_waitcnt vmcnt(0) lgkmcnt(0)
	s_barrier
.LBB0_1468:
	s_add_i32 s56, s28, 1
	v_readlane_b32 s0, v254, 14
	s_cmp_ge_u32 s56, s0
	s_cbranch_scc1 .Lrw_nd_nopf
	s_lshl_b32 s57, s56, 5
	s_sub_i32 s58, 0xe0, s57
	s_and_b64 s[50:51], s[36:37], exec
	s_cselect_b32 s64, s57, s58
	s_sub_i32 s58, 0x11e0, s57
	s_and_b64 s[50:51], s[36:37], exec
	s_cselect_b32 s50, s57, s58
	s_cmp_lt_u32 s28, 7
	s_movk_i32 s0, 0x10ff
	s_cselect_b32 s57, s64, s50
	s_cselect_b32 s58, 0xff, s0
	s_cselect_b32 s59, 0, 0x100
	s_add_i32 s66, s57, -1
	v_add_u32_e32 v30, s66, v93
	v_cmp_le_i32_e32 vcc, s59, v30
	v_cmp_ge_i32_e64 s[50:51], s58, v30
	s_and_b64 s[50:51], vcc, s[50:51]
	v_mov_b32_e32 v28, v164
	v_mov_b32_e32 v29, v164
	s_and_b64 s[68:69], s[42:43], s[50:51]
	v_mov_b64_e32 v[32:33], v[28:29]
	v_mov_b64_e32 v[34:35], v[28:29]
	s_and_saveexec_b64 s[50:51], s[68:69]
	s_cbranch_execz .LBB0_1471
	v_mov_b32_e32 v31, v164
	v_lshlrev_b64 v[30:31], 11, v[30:31]
	v_lshl_add_u64 v[30:31], v[84:85], 0, v[30:31]
	global_load_dwordx4 v[32:35], v[30:31], off

; template <bool DUAL>
; __device__ __forceinline__ void rwkv_tile(const Params& p, int l, int tile, unsigned char* smem) {
;     ...
; #pragma unroll
;     for (int k = 0; k < 2; ++k) {
;       const int i = (tid >> 4) + 16 * k;
;       const int ri = (d == 0) ? i + 1 : 32 - i;
;       const bf16_t* r0 = raw + ri * 192 + lc;
;       const bf16_t* q0 = pre + (ri - 1) * 192 + lc;
;       float rs[4], ksv[4], vs[4];
; #pragma unroll
;       for (int sl = 0; sl < 3; ++sl) {
;         const uint2 uc = *(const uint2*)(r0 + sl * 64), up = *(const uint2*)(r0 + sl * 64 - 192), un = *(const uint2*)(r0 + sl * 64 + 192);
;         const float4 m0 = (sl == 0) ? m0r : ((sl == 1) ? m0k : m0v);
;         const float4 m1 = (sl == 0) ? m1r : ((sl == 1) ? m1k : m1v);
;         float* dst = (sl == 0) ? rs : ((sl == 1) ? ksv : vs);
;         float u, a, n;
;         u = __uint_as_float(uc.x << 16); a = __uint_as_float(up.x << 16); n = __uint_as_float(un.x << 16);
;         dst[0] = u + m0.x * (a - u) + m1.x * (n - u);
;         u = __uint_as_float(uc.x & 0xffff0000u); a = __uint_as_float(up.x & 0xffff0000u); n = __uint_as_float(un.x & 0xffff0000u);
;         dst[1] = u + m0.y * (a - u) + m1.y * (n - u);
;         u = __uint_as_float(uc.y << 16); a = __uint_as_float(up.y << 16); n = __uint_as_float(un.y << 16);
;         dst[2] = u + m0.z * (a - u) + m1.z * (n - u);
;         u = __uint_as_float(uc.y & 0xffff0000u); a = __uint_as_float(up.y & 0xffff0000u); n = __uint_as_float(un.y & 0xffff0000u);
;         dst[3] = u + m0.w * (a - u) + m1.w * (n - u);
;       }
;       const uint2 ue = *(const uint2*)(q0), ua = *(const uint2*)(q0 + 64), uk = *(const uint2*)(q0 + 128);
;       const float ew[4] = {__uint_as_float(ue.x << 16), __uint_as_float(ue.x & 0xffff0000u), __uint_as_float(ue.y << 16), __uint_as_float(ue.y & 0xffff0000u)};
;       const float av[4] = {__uint_as_float(ua.x << 16), __uint_as_float(ua.x & 0xffff0000u), __uint_as_float(ua.y << 16), __uint_as_float(ua.y & 0xffff0000u)};
;       const float kk[4] = {__uint_as_float(uk.x << 16), __uint_as_float(uk.x & 0xffff0000u), __uint_as_float(uk.y << 16), __uint_as_float(uk.y & 0xffff0000u)};
;       const float kav[4] = {ka4.x, ka4.y, ka4.z, ka4.w};
;       float4 o0, o1, o2, o3, o4, o5;
.Lrw_nd_nopf:
	ds_read2_b64 v[64:67], v104 offset1:16
	ds_read_b64 v[76:77], v105
	ds_read2_b64 v[68:71], v104 offset0:32 offset1:48
	ds_read_b64 v[80:81], v106
	ds_read_b64 v[82:83], v107
	ds_read_b64 v[118:119], v108 offset:12928
	ds_read2_b64 v[72:75], v104 offset0:64 offset1:80
	s_waitcnt lgkmcnt(6)
	v_lshlrev_b32_e32 v78, 16, v64
	v_and_b32_e32 v79, 0xffff0000, v64
	v_add_u32_e32 v64, 0x3000, v108
	v_lshlrev_b32_e32 v124, 16, v65
	v_and_b32_e32 v125, 0xffff0000, v65
	v_lshlrev_b32_e32 v128, 16, v66
	v_and_b32_e32 v129, 0xffff0000, v66
	v_lshlrev_b32_e32 v134, 16, v67
	v_and_b32_e32 v135, 0xffff0000, v67
	ds_read2_b64 v[64:67], v64 offset0:48 offset1:64
	s_waitcnt lgkmcnt(5)
	v_lshlrev_b32_e32 v138, 16, v68
	v_and_b32_e32 v139, 0xffff0000, v68
	s_waitcnt lgkmcnt(1)
	v_lshlrev_b32_e32 v132, 16, v72
	v_and_b32_e32 v133, 0xffff0000, v72
	s_waitcnt lgkmcnt(0)
	v_lshlrev_b32_e32 v68, 16, v64
	v_and_b32_e32 v64, 0xffff0000, v64
	v_lshlrev_b32_e32 v72, 16, v65
	v_mul_f32_e32 v64, 0xbfb8aa3b, v64
	v_lshlrev_b32_e32 v126, 16, v71
	v_and_b32_e32 v127, 0xffff0000, v71
	v_and_b32_e32 v65, 0xffff0000, v65
	v_exp_f32_e32 v71, v64
	v_mul_f32_e32 v64, 0xbfb8aa3b, v72
	v_mul_f32_e32 v68, 0xbfb8aa3b, v68
	v_exp_f32_e32 v72, v64
	v_mul_f32_e32 v64, 0xbfb8aa3b, v65
	v_lshlrev_b32_e32 v122, 16, v70
	v_and_b32_e32 v123, 0xffff0000, v70
	v_lshlrev_b32_e32 v136, 16, v73
	v_and_b32_e32 v137, 0xffff0000, v73
	v_exp_f32_e32 v70, v68
	v_exp_f32_e32 v73, v64
	v_lshlrev_b32_e32 v117, 16, v66
	v_lshlrev_b32_e32 v146, 16, v119
	v_lshlrev_b32_e32 v149, 16, v67
	ds_write_b128 v115, v[70:73] offset:25344
	v_and_b32_e32 v71, 16, v66
	v_and_b32_e32 v70, 0xffff0000, v118
	v_lshlrev_b32_e32 v72, 16, v118
	v_and_b32_e32 v73, 0xffff0000, v66
	v_pk_mov_b32 v[64:65], v[116:117], v[70:71] op_sel:[1,0]
	v_and_b32_e32 v151, 16, v67
	v_and_b32_e32 v150, 0xffff0000, v119
	v_lshlrev_b32_e32 v130, 16, v80
	v_and_b32_e32 v131, 0xffff0000, v80
	v_lshlrev_b32_e32 v144, 16, v69
	v_and_b32_e32 v145, 0xffff0000, v69
	v_pk_mul_f32 v[64:65], v[72:73], v[64:65]
	v_and_b32_e32 v147, 0xffff0000, v67
	v_pk_mov_b32 v[66:67], v[148:149], v[150:151] op_sel:[1,0]
	v_mov_b32_e32 v68, v72
	v_mov_b32_e32 v69, v70
	v_mov_b32_e32 v70, v146
	v_mov_b32_e32 v71, v150
	v_pk_mul_f32 v[66:67], v[146:147], v[66:67]
	ds_write_b128 v115, v[68:71] offset:25600
	ds_write_b128 v115, v[64:67] offset:25856
	v_pk_add_f32 v[64:65], v[130:131], v[128:129] neg_lo:[0,1] neg_hi:[0,1]
	v_pk_add_f32 v[66:67], v[132:133], v[128:129] neg_lo:[0,1] neg_hi:[0,1]

; template <bool DUAL>
; __device__ __forceinline__ void rwkv_tile(const Params& p, int l, int tile, unsigned char* smem) {
;     ...
;       for (int sl = 0; sl < 3; ++sl) {
;         const uint2 uc = *(const uint2*)(r0 + sl * 64), up = *(const uint2*)(r0 + sl * 64 - 192), un = *(const uint2*)(r0 + sl * 64 + 192);
;         const float4 m0 = (sl == 0) ? m0r : ((sl == 1) ? m0k : m0v);
;         const float4 m1 = (sl == 0) ? m1r : ((sl == 1) ? m1k : m1v);
;         float* dst = (sl == 0) ? rs : ((sl == 1) ? ksv : vs);
;         float u, a, n;
;         u = __uint_as_float(uc.x << 16); a = __uint_as_float(up.x << 16); n = __uint_as_float(un.x << 16);
;         dst[0] = u + m0.x * (a - u) + m1.x * (n - u);
;         u = __uint_as_float(uc.x & 0xffff0000u); a = __uint_as_float(up.x & 0xffff0000u); n = __uint_as_float(un.x & 0xffff0000u);
;         dst[1] = u + m0.y * (a - u) + m1.y * (n - u);
;         u = __uint_as_float(uc.y << 16); a = __uint_as_float(up.y << 16); n = __uint_as_float(un.y << 16);
;         dst[2] = u + m0.z * (a - u) + m1.z * (n - u);
;         u = __uint_as_float(uc.y & 0xffff0000u); a = __uint_as_float(up.y & 0xffff0000u); n = __uint_as_float(un.y & 0xffff0000u);
;         dst[3] = u + m0.w * (a - u) + m1.w * (n - u);
;       }
;       const uint2 ue = *(const uint2*)(q0), ua = *(const uint2*)(q0 + 64), uk = *(const uint2*)(q0 + 128);
;       const float ew[4] = {__uint_as_float(ue.x << 16), __uint_as_float(ue.x & 0xffff0000u), __uint_as_float(ue.y << 16), __uint_as_float(ue.y & 0xffff0000u)};
;       const float av[4] = {__uint_as_float(ua.x << 16), __uint_as_float(ua.x & 0xffff0000u), __uint_as_float(ua.y << 16), __uint_as_float(ua.y & 0xffff0000u)};
;       const float kk[4] = {__uint_as_float(uk.x << 16), __uint_as_float(uk.x & 0xffff0000u), __uint_as_float(uk.y << 16), __uint_as_float(uk.y & 0xffff0000u)};
;       const float kav[4] = {ka4.x, ka4.y, ka4.z, ka4.w};
;       float4 o0, o1, o2, o3, o4, o5;
;       float* f0 = (float*)&o0; float* f1 = (float*)&o1; float* f2 = (float*)&o2; float* f3 = (float*)&o3; float* f4 = (float*)&o4; float* f5 = (float*)&o5;
; #pragma unroll
;       for (int e = 0; e < 4; ++e) {
;         f0[e] = __expf(-ew[e]);
;         f1[e] = kk[e];
;         f2[e] = kk[e] * av[e];
;         f3[e] = ksv[e] * (1.f + (av[e] - 1.f) * kav[e]);
	v_pk_fma_f32 v[64:65], v[12:13], v[64:65], v[128:129]
	v_mov_b32_e32 v72, v117

; template <bool DUAL>
; __device__ __forceinline__ void rwkv_tile(const Params& p, int l, int tile, unsigned char* smem) {
;     ...
;       for (int sl = 0; sl < 3; ++sl) {
;         const uint2 uc = *(const uint2*)(r0 + sl * 64), up = *(const uint2*)(r0 + sl * 64 - 192), un = *(const uint2*)(r0 + sl * 64 + 192);
;         const float4 m0 = (sl == 0) ? m0r : ((sl == 1) ? m0k : m0v);
;         const float4 m1 = (sl == 0) ? m1r : ((sl == 1) ? m1k : m1v);
;         float* dst = (sl == 0) ? rs : ((sl == 1) ? ksv : vs);
;         float u, a, n;
;         u = __uint_as_float(uc.x << 16); a = __uint_as_float(up.x << 16); n = __uint_as_float(un.x << 16);
;         dst[0] = u + m0.x * (a - u) + m1.x * (n - u);
;         u = __uint_as_float(uc.x & 0xffff0000u); a = __uint_as_float(up.x & 0xffff0000u); n = __uint_as_float(un.x & 0xffff0000u);
;         dst[1] = u + m0.y * (a - u) + m1.y * (n - u);
;         u = __uint_as_float(uc.y << 16); a = __uint_as_float(up.y << 16); n = __uint_as_float(un.y << 16);
;         dst[2] = u + m0.z * (a - u) + m1.z * (n - u);
;         u = __uint_as_float(uc.y & 0xffff0000u); a = __uint_as_float(up.y & 0xffff0000u); n = __uint_as_float(un.y & 0xffff0000u);
;         dst[3] = u + m0.w * (a - u) + m1.w * (n - u);
;       }
;       const uint2 ue = *(const uint2*)(q0), ua = *(const uint2*)(q0 + 64), uk = *(const uint2*)(q0 + 128);
;       const float ew[4] = {__uint_as_float(ue.x << 16), __uint_as_float(ue.x & 0xffff0000u), __uint_as_float(ue.y << 16), __uint_as_float(ue.y & 0xffff0000u)};
;       const float av[4] = {__uint_as_float(ua.x << 16), __uint_as_float(ua.x & 0xffff0000u), __uint_as_float(ua.y << 16), __uint_as_float(ua.y & 0xffff0000u)};
;       const float kk[4] = {__uint_as_float(uk.x << 16), __uint_as_float(uk.x & 0xffff0000u), __uint_as_float(uk.y << 16), __uint_as_float(uk.y & 0xffff0000u)};
;       const float kav[4] = {ka4.x, ka4.y, ka4.z, ka4.w};
;       float4 o0, o1, o2, o3, o4, o5;
;       float* f0 = (float*)&o0; float* f1 = (float*)&o1; float* f2 = (float*)&o2; float* f3 = (float*)&o3; float* f4 = (float*)&o4; float* f5 = (float*)&o5;
; #pragma unroll
;       for (int e = 0; e < 4; ++e) {
;         f0[e] = __expf(-ew[e]);
;         f1[e] = kk[e];
;         f2[e] = kk[e] * av[e];
;         f3[e] = ksv[e] * (1.f + (av[e] - 1.f) * kav[e]);
	v_pk_fma_f32 v[64:65], v[20:21], v[66:67], v[64:65]
	v_pk_add_f32 v[66:67], v[72:73], -1.0 op_sel_hi:[1,0]
	v_lshlrev_b32_e32 v80, 16, v81
	v_and_b32_e32 v81, 0xffff0000, v81

; template <bool DUAL>
; __device__ __forceinline__ void rwkv_tile(const Params& p, int l, int tile, unsigned char* smem) {
;     ...
; #pragma unroll
;     for (int k = 0; k < 2; ++k) {
;       const int i = (tid >> 4) + 16 * k;
;       const int ri = (d == 0) ? i + 1 : 32 - i;
;       const bf16_t* r0 = raw + ri * 192 + lc;
;       const bf16_t* q0 = pre + (ri - 1) * 192 + lc;
;       float rs[4], ksv[4], vs[4];
; #pragma unroll
;       for (int sl = 0; sl < 3; ++sl) {
;         const uint2 uc = *(const uint2*)(r0 + sl * 64), up = *(const uint2*)(r0 + sl * 64 - 192), un = *(const uint2*)(r0 + sl * 64 + 192);
;         const float4 m0 = (sl == 0) ? m0r : ((sl == 1) ? m0k : m0v);
;         const float4 m1 = (sl == 0) ? m1r : ((sl == 1) ? m1k : m1v);
;         float* dst = (sl == 0) ? rs : ((sl == 1) ? ksv : vs);
;         float u, a, n;
;         u = __uint_as_float(uc.x << 16); a = __uint_as_float(up.x << 16); n = __uint_as_float(un.x << 16);
;         dst[0] = u + m0.x * (a - u) + m1.x * (n - u);
;         u = __uint_as_float(uc.x & 0xffff0000u); a = __uint_as_float(up.x & 0xffff0000u); n = __uint_as_float(un.x & 0xffff0000u);
;         dst[1] = u + m0.y * (a - u) + m1.y * (n - u);
;         u = __uint_as_float(uc.y << 16); a = __uint_as_float(up.y << 16); n = __uint_as_float(un.y << 16);
;         dst[2] = u + m0.z * (a - u) + m1.z * (n - u);
;         u = __uint_as_float(uc.y & 0xffff0000u); a = __uint_as_float(up.y & 0xffff0000u); n = __uint_as_float(un.y & 0xffff0000u);
;         dst[3] = u + m0.w * (a - u) + m1.w * (n - u);
;       }
;       const uint2 ue = *(const uint2*)(q0), ua = *(const uint2*)(q0 + 64), uk = *(const uint2*)(q0 + 128);
;       const float ew[4] = {__uint_as_float(ue.x << 16), __uint_as_float(ue.x & 0xffff0000u), __uint_as_float(ue.y << 16), __uint_as_float(ue.y & 0xffff0000u)};
;       const float av[4] = {__uint_as_float(ua.x << 16), __uint_as_float(ua.x & 0xffff0000u), __uint_as_float(ua.y << 16), __uint_as_float(ua.y & 0xffff0000u)};
;       const float kk[4] = {__uint_as_float(uk.x << 16), __uint_as_float(uk.x & 0xffff0000u), __uint_as_float(uk.y << 16), __uint_as_float(uk.y & 0xffff0000u)};
;       const float kav[4] = {ka4.x, ka4.y, ka4.z, ka4.w};
;       float4 o0, o1, o2, o3, o4, o5;
	v_pk_fma_f32 v[66:67], v[24:25], v[66:67], 1.0 op_sel_hi:[1,1,0]
	v_pk_add_f32 v[68:69], v[136:137], v[134:135] neg_lo:[0,1] neg_hi:[0,1]
	v_pk_mul_f32 v[64:65], v[64:65], v[66:67]
	v_pk_add_f32 v[66:67], v[80:81], v[134:135] neg_lo:[0,1] neg_hi:[0,1]
	v_mov_b32_e32 v146, v149
	v_pk_fma_f32 v[66:67], v[14:15], v[66:67], v[134:135]
	v_lshlrev_b32_e32 v120, 16, v76
	v_pk_fma_f32 v[66:67], v[22:23], v[68:69], v[66:67]
	v_pk_add_f32 v[68:69], v[146:147], -1.0 op_sel_hi:[1,0]
	v_and_b32_e32 v121, 0xffff0000, v76
	v_pk_fma_f32 v[68:69], v[26:27], v[68:69], 1.0 op_sel_hi:[1,1,0]
	v_lshlrev_b32_e32 v76, 16, v77
	v_pk_mul_f32 v[66:67], v[66:67], v[68:69]
	ds_write_b128 v115, v[64:67] offset:26112
	v_pk_add_f32 v[64:65], v[120:121], v[78:79] neg_lo:[0,1] neg_hi:[0,1]
	v_and_b32_e32 v77, 0xffff0000, v77
	v_pk_fma_f32 v[64:65], v[8:9], v[64:65], v[78:79]
	v_pk_add_f32 v[66:67], v[122:123], v[78:79] neg_lo:[0,1] neg_hi:[0,1]
	v_pk_add_f32 v[68:69], v[126:127], v[124:125] neg_lo:[0,1] neg_hi:[0,1]
	v_pk_fma_f32 v[64:65], v[0:1], v[66:67], v[64:65]
	v_pk_add_f32 v[66:67], v[76:77], v[124:125] neg_lo:[0,1] neg_hi:[0,1]
	v_lshlrev_b32_e32 v140, 16, v82
	v_pk_fma_f32 v[66:67], v[10:11], v[66:67], v[124:125]
	v_and_b32_e32 v141, 0xffff0000, v82
	v_pk_fma_f32 v[66:67], v[2:3], v[68:69], v[66:67]
	v_lshlrev_b32_e32 v142, 16, v74
	v_and_b32_e32 v143, 0xffff0000, v74
	ds_write_b128 v115, v[64:67] offset:26368
	v_pk_add_f32 v[64:65], v[140:141], v[138:139] neg_lo:[0,1] neg_hi:[0,1]
	v_lshlrev_b32_e32 v82, 16, v83
	v_and_b32_e32 v83, 0xffff0000, v83
	v_pk_fma_f32 v[64:65], v[4:5], v[64:65], v[138:139]
	v_pk_add_f32 v[66:67], v[142:143], v[138:139] neg_lo:[0,1] neg_hi:[0,1]
	v_lshlrev_b32_e32 v74, 16, v75
	v_and_b32_e32 v75, 0xffff0000, v75
	v_pk_fma_f32 v[64:65], v[16:17], v[66:67], v[64:65]
	v_pk_add_f32 v[66:67], v[82:83], v[144:145] neg_lo:[0,1] neg_hi:[0,1]
	v_pk_add_f32 v[68:69], v[74:75], v[144:145] neg_lo:[0,1] neg_hi:[0,1]
	v_pk_fma_f32 v[66:67], v[6:7], v[66:67], v[144:145]
	s_add_i32 s56, s28, 1
	v_pk_fma_f32 v[66:67], v[18:19], v[68:69], v[66:67]
	ds_write_b128 v115, v[64:67] offset:26624
	ds_read2_b64 v[64:67], v109 offset1:16
	ds_read_b64 v[76:77], v110
	ds_read2_b64 v[68:71], v109 offset0:32 offset1:48
	ds_read_b64 v[80:81], v111
	ds_read_b64 v[82:83], v112
	ds_read_b64 v[118:119], v113 offset:12928
	ds_read2_b64 v[72:75], v109 offset0:64 offset1:80
	s_waitcnt lgkmcnt(6)
	v_lshlrev_b32_e32 v78, 16, v64
	v_and_b32_e32 v79, 0xffff0000, v64
	v_add_u32_e32 v64, 0x3000, v113
	v_lshlrev_b32_e32 v124, 16, v65
	v_and_b32_e32 v125, 0xffff0000, v65
	v_lshlrev_b32_e32 v128, 16, v66
	v_and_b32_e32 v129, 0xffff0000, v66
	v_lshlrev_b32_e32 v134, 16, v67
	v_and_b32_e32 v135, 0xffff0000, v67
	ds_read2_b64 v[64:67], v64 offset0:48 offset1:64
	s_waitcnt lgkmcnt(5)
	v_lshlrev_b32_e32 v138, 16, v68
	v_and_b32_e32 v139, 0xffff0000, v68
	s_waitcnt lgkmcnt(1)
	v_lshlrev_b32_e32 v132, 16, v72
	v_and_b32_e32 v133, 0xffff0000, v72
	s_waitcnt lgkmcnt(0)
; template <bool DUAL>
; __device__ __forceinline__ void rwkv_tile(const Params& p, int l, int tile, unsigned char* smem) {
;     ...
; #pragma unroll
;     for (int k = 0; k < 2; ++k) {
;       const int i = (tid >> 4) + 16 * k;
;       const int ri = (d == 0) ? i + 1 : 32 - i;
;       const bf16_t* r0 = raw + ri * 192 + lc;
;       const bf16_t* q0 = pre + (ri - 1) * 192 + lc;
;       float rs[4], ksv[4], vs[4];
; #pragma unroll
;       for (int sl = 0; sl < 3; ++sl) {
;         const uint2 uc = *(const uint2*)(r0 + sl * 64), up = *(const uint2*)(r0 + sl * 64 - 192), un = *(const uint2*)(r0 + sl * 64 + 192);
;         const float4 m0 = (sl == 0) ? m0r : ((sl == 1) ? m0k : m0v);
;         const float4 m1 = (sl == 0) ? m1r : ((sl == 1) ? m1k : m1v);
;         float* dst = (sl == 0) ? rs : ((sl == 1) ? ksv : vs);
;         float u, a, n;
;         u = __uint_as_float(uc.x << 16); a = __uint_as_float(up.x << 16); n = __uint_as_float(un.x << 16);
;         dst[0] = u + m0.x * (a - u) + m1.x * (n - u);
;         u = __uint_as_float(uc.x & 0xffff0000u); a = __uint_as_float(up.x & 0xffff0000u); n = __uint_as_float(un.x & 0xffff0000u);
;         dst[1] = u + m0.y * (a - u) + m1.y * (n - u);
;         u = __uint_as_float(uc.y << 16); a = __uint_as_float(up.y << 16); n = __uint_as_float(un.y << 16);
;         dst[2] = u + m0.z * (a - u) + m1.z * (n - u);
;         u = __uint_as_float(uc.y & 0xffff0000u); a = __uint_as_float(up.y & 0xffff0000u); n = __uint_as_float(un.y & 0xffff0000u);
;         dst[3] = u + m0.w * (a - u) + m1.w * (n - u);
;       }
;       const uint2 ue = *(const uint2*)(q0), ua = *(const uint2*)(q0 + 64), uk = *(const uint2*)(q0 + 128);
;       const float ew[4] = {__uint_as_float(ue.x << 16), __uint_as_float(ue.x & 0xffff0000u), __uint_as_float(ue.y << 16), __uint_as_float(ue.y & 0xffff0000u)};
;       const float av[4] = {__uint_as_float(ua.x << 16), __uint_as_float(ua.x & 0xffff0000u), __uint_as_float(ua.y << 16), __uint_as_float(ua.y & 0xffff0000u)};
;       const float kk[4] = {__uint_as_float(uk.x << 16), __uint_as_float(uk.x & 0xffff0000u), __uint_as_float(uk.y << 16), __uint_as_float(uk.y & 0xffff0000u)};
;       const float kav[4] = {ka4.x, ka4.y, ka4.z, ka4.w};
;       float4 o0, o1, o2, o3, o4, o5;
	v_lshlrev_b32_e32 v68, 16, v64
	v_and_b32_e32 v64, 0xffff0000, v64
	v_lshlrev_b32_e32 v72, 16, v65
	v_mul_f32_e32 v64, 0xbfb8aa3b, v64
	v_lshlrev_b32_e32 v126, 16, v71
	v_and_b32_e32 v127, 0xffff0000, v71
	v_and_b32_e32 v65, 0xffff0000, v65
	v_exp_f32_e32 v71, v64
	v_mul_f32_e32 v64, 0xbfb8aa3b, v72
	v_mul_f32_e32 v68, 0xbfb8aa3b, v68
	v_exp_f32_e32 v72, v64
	v_mul_f32_e32 v64, 0xbfb8aa3b, v65
	v_lshlrev_b32_e32 v122, 16, v70
	v_and_b32_e32 v123, 0xffff0000, v70
	v_lshlrev_b32_e32 v136, 16, v73
	v_and_b32_e32 v137, 0xffff0000, v73
	v_exp_f32_e32 v70, v68
	v_exp_f32_e32 v73, v64
	v_lshlrev_b32_e32 v117, 16, v66
	v_lshlrev_b32_e32 v146, 16, v119
	v_lshlrev_b32_e32 v149, 16, v67
	ds_write_b128 v115, v[70:73] offset:49920
	v_and_b32_e32 v71, 16, v66
	v_and_b32_e32 v70, 0xffff0000, v118
	v_lshlrev_b32_e32 v72, 16, v118
	v_and_b32_e32 v73, 0xffff0000, v66
	v_pk_mov_b32 v[64:65], v[116:117], v[70:71] op_sel:[1,0]
	v_and_b32_e32 v151, 16, v67
	v_and_b32_e32 v150, 0xffff0000, v119
	v_lshlrev_b32_e32 v130, 16, v80
	v_and_b32_e32 v131, 0xffff0000, v80
	v_lshlrev_b32_e32 v144, 16, v69
	v_and_b32_e32 v145, 0xffff0000, v69
	v_pk_mul_f32 v[64:65], v[72:73], v[64:65]
	v_and_b32_e32 v147, 0xffff0000, v67
	v_pk_mov_b32 v[66:67], v[148:149], v[150:151] op_sel:[1,0]
	v_mov_b32_e32 v68, v72
	v_mov_b32_e32 v69, v70
	v_mov_b32_e32 v70, v146
	v_mov_b32_e32 v71, v150
	v_pk_mul_f32 v[66:67], v[146:147], v[66:67]
	ds_write_b128 v115, v[68:71] offset:50176
	ds_write_b128 v115, v[64:67] offset:50432
	v_pk_add_f32 v[64:65], v[130:131], v[128:129] neg_lo:[0,1] neg_hi:[0,1]
	v_pk_add_f32 v[66:67], v[132:133], v[128:129] neg_lo:[0,1] neg_hi:[0,1]
	v_pk_fma_f32 v[64:65], v[12:13], v[64:65], v[128:129]
	v_mov_b32_e32 v72, v117
	v_pk_fma_f32 v[64:65], v[20:21], v[66:67], v[64:65]
	v_pk_add_f32 v[66:67], v[72:73], -1.0 op_sel_hi:[1,0]
	v_lshlrev_b32_e32 v80, 16, v81
	v_and_b32_e32 v81, 0xffff0000, v81
	v_pk_fma_f32 v[66:67], v[24:25], v[66:67], 1.0 op_sel_hi:[1,1,0]
	v_pk_add_f32 v[68:69], v[136:137], v[134:135] neg_lo:[0,1] neg_hi:[0,1]
	v_pk_mul_f32 v[64:65], v[64:65], v[66:67]
	v_pk_add_f32 v[66:67], v[80:81], v[134:135] neg_lo:[0,1] neg_hi:[0,1]
	v_mov_b32_e32 v146, v149
	v_pk_fma_f32 v[66:67], v[14:15], v[66:67], v[134:135]
	v_lshlrev_b32_e32 v120, 16, v76
	v_pk_fma_f32 v[66:67], v[22:23], v[68:69], v[66:67]
	v_pk_add_f32 v[68:69], v[146:147], -1.0 op_sel_hi:[1,0]
	v_and_b32_e32 v121, 0xffff0000, v76
	v_pk_fma_f32 v[68:69], v[26:27], v[68:69], 1.0 op_sel_hi:[1,1,0]
	v_lshlrev_b32_e32 v76, 16, v77
	v_pk_mul_f32 v[66:67], v[66:67], v[68:69]
	ds_write_b128 v115, v[64:67] offset:50688
	v_pk_add_f32 v[64:65], v[120:121], v[78:79] neg_lo:[0,1] neg_hi:[0,1]
	v_and_b32_e32 v77, 0xffff0000, v77
	v_pk_fma_f32 v[64:65], v[8:9], v[64:65], v[78:79]
	v_pk_add_f32 v[66:67], v[122:123], v[78:79] neg_lo:[0,1] neg_hi:[0,1]
	v_pk_add_f32 v[68:69], v[126:127], v[124:125] neg_lo:[0,1] neg_hi:[0,1]
	v_pk_fma_f32 v[64:65], v[0:1], v[66:67], v[64:65]
	v_pk_add_f32 v[66:67], v[76:77], v[124:125] neg_lo:[0,1] neg_hi:[0,1]
	v_lshlrev_b32_e32 v140, 16, v82
	v_pk_fma_f32 v[66:67], v[10:11], v[66:67], v[124:125]
	v_and_b32_e32 v141, 0xffff0000, v82
	v_pk_fma_f32 v[66:67], v[2:3], v[68:69], v[66:67]
	v_lshlrev_b32_e32 v142, 16, v74
	v_and_b32_e32 v143, 0xffff0000, v74
	ds_write_b128 v115, v[64:67] offset:50944
	v_pk_add_f32 v[64:65], v[140:141], v[138:139] neg_lo:[0,1] neg_hi:[0,1]
	v_readlane_b32 s0, v254, 14
	v_lshlrev_b32_e32 v82, 16, v83
	v_and_b32_e32 v83, 0xffff0000, v83
	v_pk_fma_f32 v[64:65], v[4:5], v[64:65], v[138:139]
	v_pk_add_f32 v[66:67], v[142:143], v[138:139] neg_lo:[0,1] neg_hi:[0,1]
	s_cmp_lt_u32 s56, s0
	v_lshlrev_b32_e32 v74, 16, v75
	v_and_b32_e32 v75, 0xffff0000, v75
	v_pk_fma_f32 v[64:65], v[16:17], v[66:67], v[64:65]
	v_pk_add_f32 v[66:67], v[82:83], v[144:145] neg_lo:[0,1] neg_hi:[0,1]
	s_cselect_b64 s[54:55], -1, 0
	s_cmp_ge_u32 s56, s0
	v_pk_fma_f32 v[66:67], v[6:7], v[66:67], v[144:145]
	v_pk_add_f32 v[68:69], v[74:75], v[144:145] neg_lo:[0,1] neg_hi:[0,1]
	s_cselect_b64 s[52:53], -1, 0
	v_pk_fma_f32 v[66:67], v[18:19], v[68:69], v[66:67]
	s_and_b64 vcc, exec, s[52:53]
	ds_write_b128 v115, v[64:67] offset:51200
	s_waitcnt lgkmcnt(0)
	s_barrier
